# retention jt loop software-pipelined: next iteration's 8 K-row loads issued right after this iteration's QK MFMAs (SGPR base + 32-bit lane offset), V fragments 7/8 reuse fragment registers 1/2
# speedup vs baseline: 1.0078x; 1.0078x over previous
; #define LAS __attribute__((address_space(3)))
; __device__ __forceinline__ void main_unit(LAS unsigned char* lds, const bf16_t* __restrict__ proj, const bf16_t* __restrict__ sprevT, bf16_t* __restrict__ y,
;                                           const float* __restrict__ rnorm, int b, int h, int n) {
;     int tid = threadIdx.x; asm volatile("" : "+v"(tid));
;     const int lane = tid & 63, wid = __builtin_amdgcn_readfirstlane(tid >> 6);
;     const int ig = wid & 3, dh = wid >> 2, r = lane & 31, hh = lane >> 5, g16 = (lane >> 4) & 1, q4 = (lane & 15) >> 2, p4 = lane & 3;
;     const size_t row0 = (size_t)b * LTOK + (size_t)n * CH;
;     const float l2g = log2gamma(h);
;     const int iloc = ig * 32 + r;
;     __syncthreads();
; #pragma unroll
;     for (int i = 0; i < 8; ++i) {
;         const int j = (tid >> 5) + 16 * i, c = tid & 31;
;         const u32x4 vv = *(const u32x4*)(proj + (row0 + j) * DIN + C_RV + h * 256 + c * 8);
;         *(LAS u32x4*)(lds + M_V + j * VSTR + c * 16) = vv;
;     }
;     bf16x8 qf[8];
;     { const bf16_t* qp = proj + (row0 + iloc) * DIN + C_RQ + h * 128 + hh * 8;
; #pragma unroll
;       for (int s = 0; s < 8; ++s) qf[s] = *(const bf16x8*)(qp + s * 16); }
;     f32x16 acc[4];
; #pragma unroll
;     for (int t = 0; t < 4; ++t) acc[t] = zero16();
;     { const bf16_t* sp = sprevT + ((size_t)((b * 4 + h) * NCH + n)) * 32768 + (size_t)(dh * 128 + r) * 128 + hh * 8;
;       bf16x8 sa[8][4];
; #pragma unroll
;       for (int s = 0; s < 8; ++s)
; #pragma unroll
;           for (int t = 0; t < 4; ++t) sa[s][t] = *(const bf16x8*)(sp + (size_t)t * 32 * 128 + s * 16);
; #pragma unroll
;       for (int s = 0; s < 8; ++s)
; #pragma unroll
; __global__ void __launch_bounds__(512, 2) hymba_fwd(Args a) {
;     ...
;                 for (;;) {
;                     if (tid == 0) *slot = ulo + (int)atomicAdd(ctl + 16 * l + 4 * rep + pass, 1u);
;                     __syncthreads();
;                     const int u = *slot;
;                     if (u >= uhi) break;
;                     if (u < 256 || u >= 256 + 528) { const int w = u < 256 ? u : u - 528; att::attn_unit(lds, proj, ybuf, w & 3, (w >> 2) & 7, 32 - (w >> 5), lam, a.attn_subln + l * 128, 1.0f - lam_init, ctl + 1536 + l * 64); }
;                     else { const int v = u - 256; ret::main_unit(lds, proj, sprevT, ybuf, a.ret_norm + l * 256, v & 3, (v >> 2) & 3, v >> 4); }
.LBB0_389:
	s_or_b64 exec, exec, s[14:15]
	v_mov_b32_e32 v0, s36
	s_waitcnt lgkmcnt(0)
	s_barrier
	ds_read_b32 v0, v0
	s_movk_i32 s1, 0x62f
	s_mov_b64 s[14:15], -1
	s_waitcnt lgkmcnt(0)
	v_cmp_lt_i32_e32 vcc, s1, v0
	v_readfirstlane_b32 s0, v0
	s_cbranch_vccnz .LBB0_384
	s_add_i32 s1, s0, 0xfffffcf0
	s_cmp_gt_u32 s1, 0xfffffdef
	s_cbranch_scc0 .LBB0_396
	s_add_i32 s1, s0, 0xffffff00
	s_and_b32 s18, s0, 3
	s_lshr_b32 s1, s1, 4
	v_mov_b32_e32 v74, v208
	s_mul_i32 s2, s18, 0x1080
	s_lshl_b32 s11, s1, 7
	v_ashrrev_i32_e32 v144, 5, v74
	s_add_i32 s16, s11, s2
	s_mov_b32 s17, s9
	v_ashrrev_i32_e32 v145, 31, v144
	s_waitcnt vmcnt(0)
	v_lshl_add_u64 v[140:141], v[144:145], 0, s[16:17]
	v_mov_b64_e32 v[2:3], s[6:7]
	s_bfe_u32 s19, s0, 0x20002
	v_mad_u64_u32 v[146:147], s[20:21], v140, s35, v[2:3]
	v_and_b32_e32 v149, 31, v74
	v_mad_i32_i24 v147, v141, s35, v147
	s_lshl_b32 s8, s19, 9
	v_lshlrev_b32_e32 v0, 4, v149
	v_lshl_add_u64 v[4:5], v[146:147], 0, s[8:9]
	s_movk_i32 s22, 0x240
	v_lshl_add_u64 v[66:67], v[4:5], 0, v[0:1]
	v_mul_lo_u32 v4, v144, s22
	v_add3_u32 v75, 0, v0, v4
	v_add_u32_e32 v4, 16, v144
	v_ashrrev_i32_e32 v5, 31, v4
	v_lshl_add_u64 v[136:137], v[4:5], 0, s[16:17]
	v_mad_u64_u32 v[142:143], s[20:21], v136, s35, v[2:3]
	v_mad_i32_i24 v143, v137, s35, v143
	v_lshl_add_u64 v[4:5], v[142:143], 0, s[8:9]
	v_lshl_add_u64 v[68:69], v[4:5], 0, v[0:1]
	v_add_u32_e32 v4, 32, v144
	v_ashrrev_i32_e32 v5, 31, v4
	v_lshl_add_u64 v[132:133], v[4:5], 0, s[16:17]
	v_mad_u64_u32 v[138:139], s[20:21], v132, s35, v[2:3]
	v_mad_i32_i24 v139, v133, s35, v139
	v_lshl_add_u64 v[4:5], v[138:139], 0, s[8:9]
	v_lshl_add_u64 v[70:71], v[4:5], 0, v[0:1]
	v_add_u32_e32 v4, 48, v144
	v_ashrrev_i32_e32 v5, 31, v4
	v_lshl_add_u64 v[128:129], v[4:5], 0, s[16:17]
	v_mad_u64_u32 v[134:135], s[20:21], v128, s35, v[2:3]
	v_mad_i32_i24 v135, v129, s35, v135
	v_lshl_add_u64 v[4:5], v[134:135], 0, s[8:9]
	v_lshl_add_u64 v[72:73], v[4:5], 0, v[0:1]
	v_add_u32_e32 v4, 64, v144
	v_ashrrev_i32_e32 v5, 31, v4
	v_lshl_add_u64 v[124:125], v[4:5], 0, s[16:17]
	v_mad_u64_u32 v[130:131], s[20:21], v124, s35, v[2:3]
	v_mad_i32_i24 v131, v125, s35, v131
	v_lshl_add_u64 v[4:5], v[130:131], 0, s[8:9]
	v_lshl_add_u64 v[80:81], v[4:5], 0, v[0:1]
	v_add_u32_e32 v4, 0x50, v144
	v_ashrrev_i32_e32 v5, 31, v4
	v_lshl_add_u64 v[120:121], v[4:5], 0, s[16:17]
	v_mad_u64_u32 v[126:127], s[20:21], v120, s35, v[2:3]
	v_mad_i32_i24 v127, v121, s35, v127
	v_lshl_add_u64 v[4:5], v[126:127], 0, s[8:9]
	v_lshl_add_u64 v[158:159], v[4:5], 0, v[0:1]
	v_add_u32_e32 v4, 0x60, v144
	v_ashrrev_i32_e32 v5, 31, v4
	v_lshl_add_u64 v[116:117], v[4:5], 0, s[16:17]
	v_mad_u64_u32 v[122:123], s[20:21], v116, s35, v[2:3]
	v_mad_i32_i24 v123, v117, s35, v123
	v_lshl_add_u64 v[4:5], v[122:123], 0, s[8:9]
	v_lshl_add_u64 v[182:183], v[4:5], 0, v[0:1]
	v_add_u32_e32 v4, 0x70, v144
	v_ashrrev_i32_e32 v5, 31, v4
	v_readfirstlane_b32 s10, v74
	v_lshl_add_u64 v[114:115], v[4:5], 0, s[16:17]
	s_bfe_u32 s3, s10, 0x20006
	v_mad_u64_u32 v[118:119], s[20:21], v114, s35, v[2:3]
	s_lshl_b32 s11, s3, 5
	v_mad_i32_i24 v119, v115, s35, v119
	v_lshl_add_u64 v[2:3], v[118:119], 0, s[8:9]
	v_or_b32_e32 v145, s11, v149
	v_lshl_add_u64 v[190:191], v[2:3], 0, v[0:1]
	v_or_b32_e32 v0, s16, v145
	v_mul_lo_u32 v0, v0, s35
	s_lshl_b32 s14, s19, 8
	s_mov_b32 s15, s9
	v_lshl_add_u64 v[2:3], s[6:7], 0, v[0:1]
	v_lshl_add_u64 v[2:3], v[2:3], 0, s[14:15]
	s_lshl_b32 s15, s18, 2
	s_or_b32 s15, s15, s19
	s_mul_i32 s15, s15, 33
	s_add_i32 s15, s15, s1
	s_add_i32 s2, s19, 5
	s_lshl_b32 s17, s19, 7
	s_lshl_b32 s1, s15, 16
	s_add_u32 s18, s78, s1
	v_bfe_u32 v148, v74, 5, 1
	s_addc_u32 s19, s79, 0
	s_ashr_i32 s1, s10, 1
	v_lshlrev_b32_e32 v0, 4, v148
	s_and_b32 s1, s1, 0xffffff80
	v_lshl_add_u64 v[18:19], v[2:3], 0, v[0:1]
	v_or_b32_e32 v2, s1, v149
	v_ashrrev_i32_e32 v3, 31, v2
	v_lshlrev_b64 v[2:3], 8, v[2:3]
	v_lshl_add_u64 v[2:3], s[18:19], 0, v[2:3]
	v_lshl_add_u64 v[174:175], v[2:3], 0, v[0:1]
	s_barrier
	global_load_dwordx4 v[2:5], v[174:175], off
	v_add_co_u32_e32 v6, vcc, s74, v18
	s_movk_i32 s8, 0x4000
	s_nop 0
	v_addc_co_u32_e32 v7, vcc, 0, v19, vcc
	global_load_dwordx4 v[82:85], v[6:7], off offset:2048
	v_add_co_u32_e32 v176, vcc, s68, v174
	s_mov_b64 s[18:19], 0x1800
	s_nop 0
	v_addc_co_u32_e32 v177, vcc, 0, v175, vcc
	v_add_co_u32_e32 v186, vcc, s8, v174
	s_movk_i32 s8, 0x6000
	s_nop 0
	v_addc_co_u32_e32 v187, vcc, 0, v175, vcc
	global_load_dwordx4 v[6:9], v[176:177], off
	v_add_co_u32_e32 v192, vcc, s8, v174
	global_load_dwordx4 v[10:13], v[186:187], off
	s_nop 0
	v_addc_co_u32_e32 v193, vcc, 0, v175, vcc
	global_load_dwordx4 v[14:17], v[192:193], off
	global_load_dwordx4 v[76:79], v[174:175], off offset:32
	v_lshl_add_u64 v[178:179], v[18:19], 0, s[18:19]
	global_load_dwordx4 v[86:89], v[178:179], off offset:32
	global_load_dwordx4 v[98:101], v[176:177], off offset:32
	global_load_dwordx4 v[90:93], v[178:179], off offset:224
	global_load_dwordx4 v[102:105], v[186:187], off offset:32
	global_load_dwordx4 v[106:109], v[192:193], off offset:32
	global_load_dwordx4 v[110:113], v[174:175], off offset:64
	global_load_dwordx4 v[94:97], v[178:179], off offset:64
	global_load_dwordx4 v[150:153], v[176:177], off offset:64
	global_load_dwordx4 v[154:157], v[192:193], off offset:64
	v_add_co_u32_e32 v66, vcc, s68, v66
	v_cvt_f32_ubyte0_e32 v0, s2
	s_nop 0
	v_addc_co_u32_e32 v67, vcc, 0, v67, vcc
	v_exp_f32_e64 v0, -v0
	s_mulk_i32 s3, 0x4800
	s_waitcnt vmcnt(13)
	v_mfma_f32_32x32x16_bf16 v[50:65], v[2:5], v[82:85], 0
	v_sub_f32_e32 v0, 1.0, v0
	s_mov_b32 s2, 0
	s_waitcnt vmcnt(8)
; #define LAS __attribute__((address_space(3)))
; #define MFMA32(a, b, c) __builtin_amdgcn_mfma_f32_32x32x16_bf16((a), (b), (c), 0, 0, 0)
; __device__ __forceinline__ void main_unit(LAS unsigned char* lds, const bf16_t* __restrict__ proj, const bf16_t* __restrict__ sprevT, bf16_t* __restrict__ y,
;                                           const float* __restrict__ rnorm, int b, int h, int n) {
;     ...
; #pragma unroll
;     for (int i = 0; i < 8; ++i) {
;         const int j = (tid >> 5) + 16 * i, c = tid & 31;
;         const u32x4 vv = *(const u32x4*)(proj + (row0 + j) * DIN + C_RV + h * 256 + c * 8);
;         *(LAS u32x4*)(lds + M_V + j * VSTR + c * 16) = vv;
;     }
;     bf16x8 qf[8];
;     { const bf16_t* qp = proj + (row0 + iloc) * DIN + C_RQ + h * 128 + hh * 8;
; #pragma unroll
;       for (int s = 0; s < 8; ++s) qf[s] = *(const bf16x8*)(qp + s * 16); }
;     f32x16 acc[4];
; #pragma unroll
;     for (int t = 0; t < 4; ++t) acc[t] = zero16();
;     { const bf16_t* sp = sprevT + ((size_t)((b * 4 + h) * NCH + n)) * 32768 + (size_t)(dh * 128 + r) * 128 + hh * 8;
;       bf16x8 sa[8][4];
; #pragma unroll
;       for (int s = 0; s < 8; ++s)
; #pragma unroll
;           for (int t = 0; t < 4; ++t) sa[s][t] = *(const bf16x8*)(sp + (size_t)t * 32 * 128 + s * 16);
; #pragma unroll
;       for (int s = 0; s < 8; ++s)
; #pragma unroll
;           for (int t = 0; t < 4; ++t) acc[t] = MFMA32(sa[s][t], qf[s], acc[t]); }
;     { const float qd = __builtin_amdgcn_exp2f(l2g * (float)(iloc + 1));
; #pragma unroll
;       for (int t = 0; t < 4; ++t)
; #pragma unroll
;           for (int i = 0; i < 16; ++i) acc[t][i] *= qd; }
	v_mfma_f32_32x32x16_bf16 v[50:65], v[76:79], v[86:89], v[50:65]
	global_load_dwordx4 v[76:79], v[186:187], off offset:64
	v_mfma_f32_32x32x16_bf16 v[34:49], v[6:9], v[82:85], 0
	v_mfma_f32_32x32x16_bf16 v[18:33], v[10:13], v[82:85], 0
	v_mfma_f32_32x32x16_bf16 v[2:17], v[14:17], v[82:85], 0
	s_waitcnt vmcnt(8)
	v_mfma_f32_32x32x16_bf16 v[34:49], v[98:101], v[86:89], v[34:49]
	global_load_dwordx4 v[162:165], v[174:175], off offset:96
	global_load_dwordx4 v[98:101], v[178:179], off offset:96
	s_waitcnt vmcnt(7)
	v_mfma_f32_32x32x16_bf16 v[2:17], v[106:109], v[86:89], v[2:17]
	global_load_dwordx4 v[106:109], v[176:177], off offset:96
	v_mfma_f32_32x32x16_bf16 v[18:33], v[102:105], v[86:89], v[18:33]
	s_waitcnt vmcnt(6)
	v_mfma_f32_32x32x16_bf16 v[50:65], v[110:113], v[94:97], v[50:65]
	global_load_dwordx4 v[110:113], v[186:187], off offset:96
	s_waitcnt vmcnt(6)
	v_mfma_f32_32x32x16_bf16 v[34:49], v[150:153], v[94:97], v[34:49]
	global_load_dwordx4 v[150:153], v[192:193], off offset:96
	s_waitcnt vmcnt(5)
	v_mfma_f32_32x32x16_bf16 v[18:33], v[76:79], v[94:97], v[18:33]
	global_load_dwordx4 v[76:79], v[174:175], off offset:128
	global_load_dwordx4 v[102:105], v[178:179], off offset:128
	global_load_dwordx4 v[166:169], v[192:193], off offset:128
	v_mfma_f32_32x32x16_bf16 v[2:17], v[154:157], v[94:97], v[2:17]
	global_load_dwordx4 v[154:157], v[176:177], off offset:128
	s_waitcnt vmcnt(7)
	v_mfma_f32_32x32x16_bf16 v[50:65], v[162:165], v[98:101], v[50:65]
	global_load_dwordx4 v[162:165], v[186:187], off offset:128
	s_waitcnt vmcnt(7)
	v_mfma_f32_32x32x16_bf16 v[34:49], v[106:109], v[98:101], v[34:49]
	global_load_dwordx4 v[170:173], v[174:175], off offset:160
	global_load_dwordx4 v[106:109], v[178:179], off offset:160
	s_waitcnt vmcnt(8)
	v_mfma_f32_32x32x16_bf16 v[18:33], v[110:113], v[98:101], v[18:33]
	s_waitcnt vmcnt(7)
	v_mfma_f32_32x32x16_bf16 v[2:17], v[150:153], v[98:101], v[2:17]
	global_load_dwordx4 v[150:153], v[176:177], off offset:160
	s_waitcnt vmcnt(6)
	v_mfma_f32_32x32x16_bf16 v[50:65], v[76:79], v[102:105], v[50:65]
	global_load_dwordx4 v[76:79], v[186:187], off offset:160
	s_waitcnt vmcnt(5)
	v_mfma_f32_32x32x16_bf16 v[34:49], v[154:157], v[102:105], v[34:49]
	global_load_dwordx4 v[154:157], v[192:193], off offset:160
	s_waitcnt vmcnt(5)
	v_mfma_f32_32x32x16_bf16 v[18:33], v[162:165], v[102:105], v[18:33]
	global_load_dwordx4 v[162:165], v[174:175], off offset:192
	global_load_dwordx4 v[110:113], v[178:179], off offset:192
	v_mfma_f32_32x32x16_bf16 v[2:17], v[166:169], v[102:105], v[2:17]
	global_load_dwordx4 v[166:169], v[176:177], off offset:192
	s_waitcnt vmcnt(6)
	v_mfma_f32_32x32x16_bf16 v[50:65], v[170:173], v[106:109], v[50:65]
	global_load_dwordx4 v[170:173], v[186:187], off offset:192
	s_waitcnt vmcnt(6)
	v_mfma_f32_32x32x16_bf16 v[34:49], v[150:153], v[106:109], v[34:49]
	global_load_dwordx4 v[150:153], v[192:193], off offset:192
	s_waitcnt vmcnt(6)
	v_mfma_f32_32x32x16_bf16 v[18:33], v[76:79], v[106:109], v[18:33]
	v_add_co_u32_e32 v76, vcc, s68, v68
	s_nop 1
	v_addc_co_u32_e32 v77, vcc, 0, v69, vcc
	global_load_dwordx4 v[66:69], v[66:67], off
	s_nop 0
	global_load_dwordx4 v[76:79], v[76:77], off
	s_waitcnt vmcnt(7)
	v_mfma_f32_32x32x16_bf16 v[2:17], v[154:157], v[106:109], v[2:17]
	v_add_co_u32_e32 v154, vcc, s68, v70
	s_nop 1
	v_addc_co_u32_e32 v155, vcc, 0, v71, vcc
	v_add_co_u32_e32 v178, vcc, s68, v72
	s_waitcnt vmcnt(5)
	v_mfma_f32_32x32x16_bf16 v[50:65], v[162:165], v[110:113], v[50:65]
	v_addc_co_u32_e32 v179, vcc, 0, v73, vcc
	v_add_co_u32_e32 v80, vcc, s68, v80
	global_load_dwordx4 v[70:73], v[174:175], off offset:224
	s_nop 0
	v_addc_co_u32_e32 v81, vcc, 0, v81, vcc
	global_load_dwordx4 v[154:157], v[154:155], off
	s_nop 0
	global_load_dwordx4 v[162:165], v[178:179], off
	s_waitcnt vmcnt(7)
	v_mfma_f32_32x32x16_bf16 v[34:49], v[166:169], v[110:113], v[34:49]
	global_load_dwordx4 v[166:169], v[80:81], off
	v_add_co_u32_e32 v80, vcc, s68, v158
	global_load_dwordx4 v[174:177], v[176:177], off offset:224
	s_nop 0
	v_addc_co_u32_e32 v81, vcc, 0, v159, vcc
	global_load_dwordx4 v[178:181], v[80:81], off
	s_nop 0
	global_load_dwordx4 v[186:189], v[186:187], off offset:224
	v_add_co_u32_e32 v80, vcc, s68, v182
	s_waitcnt vmcnt(10)
	v_mfma_f32_32x32x16_bf16 v[18:33], v[170:173], v[110:113], v[18:33]
	v_addc_co_u32_e32 v81, vcc, 0, v183, vcc
	global_load_dwordx4 v[170:173], v[80:81], off
	v_add_co_u32_e32 v80, vcc, s68, v190
	s_nop 1
	v_addc_co_u32_e32 v81, vcc, 0, v191, vcc
	global_load_dwordx4 v[190:193], v[192:193], off offset:224
	s_waitcnt vmcnt(11)
	v_mfma_f32_32x32x16_bf16 v[2:17], v[150:153], v[110:113], v[2:17]
	global_load_dwordx4 v[204:207], v[80:81], off
	v_cmp_gt_f32_e32 vcc, s65, v0
	s_and_b64 s[18:19], vcc, exec
	s_cselect_b32 s15, 32, 0
	v_ldexp_f32 v0, v0, s15
	v_log_f32_e32 v0, v0
	s_waitcnt vmcnt(11)
	ds_write_b128 v75, v[66:69]
	s_waitcnt vmcnt(10)
	ds_write_b128 v75, v[76:79] offset:9216
	s_waitcnt vmcnt(8)
	ds_write_b128 v75, v[154:157] offset:18432
	s_waitcnt vmcnt(7)
	ds_write_b128 v75, v[162:165] offset:27648
	s_waitcnt vmcnt(6)
	ds_write_b128 v75, v[166:169] offset:36864
	v_mfma_f32_32x32x16_bf16 v[50:65], v[70:73], v[90:93], v[50:65]
	v_cndmask_b32_e32 v66, 0, v194, vcc
	v_sub_f32_e32 v151, v0, v66
	v_add_u32_e32 v0, 1, v145
	v_cvt_f32_ubyte0_e32 v0, v0
	v_mul_f32_e32 v0, v151, v0
	v_exp_f32_e32 v0, v0
	v_lshrrev_b32_e32 v80, 2, v74
	s_waitcnt vmcnt(5)
	v_mfma_f32_32x32x16_bf16 v[34:49], v[174:177], v[90:93], v[34:49]
	v_lshlrev_b32_e32 v152, 2, v148
	s_and_b32 s10, s10, 0xffffff00
	s_nop 0
	v_mul_f32_e64 v64, v0, v64
	v_mul_f32_e64 v65, v0, v65
	v_mul_f32_e64 v62, v0, v62
	v_mul_f32_e64 v63, v0, v63
	v_pk_mul_f32 v[60:61], v[0:1], v[60:61] op_sel_hi:[0,1]
	v_pk_mul_f32 v[58:59], v[0:1], v[58:59] op_sel_hi:[0,1]
	v_pk_mul_f32 v[56:57], v[0:1], v[56:57] op_sel_hi:[0,1]
	s_waitcnt vmcnt(3)
; #define LAS __attribute__((address_space(3)))
; #define MFMA32(a, b, c) __builtin_amdgcn_mfma_f32_32x32x16_bf16((a), (b), (c), 0, 0, 0)
; __device__ __forceinline__ void main_unit(LAS unsigned char* lds, const bf16_t* __restrict__ proj, const bf16_t* __restrict__ sprevT, bf16_t* __restrict__ y,
;                                           const float* __restrict__ rnorm, int b, int h, int n) {
;     ...
;     { const float qd = __builtin_amdgcn_exp2f(l2g * (float)(iloc + 1));
; #pragma unroll
;       for (int t = 0; t < 4; ++t)
; #pragma unroll
;           for (int i = 0; i < 16; ++i) acc[t][i] *= qd; }
;     __syncthreads();
;     const LAS unsigned char* va = lds + M_V + (4 * hh + q4) * VSTR + (dh * 128 + 16 * g16) * 2 + 8 * p4;
;     for (int jt = 0; jt <= ig; ++jt) {
;         f32x16 st = zero16();
;         const bf16_t* kp = proj + (row0 + jt * 32 + r) * DIN + C_RK + h * 128 + hh * 8;
;         bf16x8 ka[8];
; #pragma unroll
;         for (int s = 0; s < 8; ++s) ka[s] = *(const bf16x8*)(kp + s * 16);
; #pragma unroll
;         for (int s = 0; s < 8; ++s) st = MFMA32(ka[s], qf[s], st);
	v_mfma_f32_32x32x16_bf16 v[18:33], v[186:189], v[90:93], v[18:33]
	v_mul_f32_e64 v54, v0, v54
	v_mul_f32_e64 v55, v0, v55
	v_mul_f32_e64 v52, v0, v52
	v_mul_f32_e64 v53, v0, v53
	v_mul_f32_e64 v50, v0, v50
	v_mul_f32_e64 v51, v0, v51
	v_pk_mul_f32 v[48:49], v[0:1], v[48:49] op_sel_hi:[0,1]
	v_pk_mul_f32 v[46:47], v[0:1], v[46:47] op_sel_hi:[0,1]
	v_pk_mul_f32 v[44:45], v[0:1], v[44:45] op_sel_hi:[0,1]
	v_pk_mul_f32 v[42:43], v[0:1], v[42:43] op_sel_hi:[0,1]
	s_waitcnt vmcnt(1)
	v_mfma_f32_32x32x16_bf16 v[2:17], v[190:193], v[90:93], v[2:17]
	v_mul_f32_e64 v40, v0, v40
	v_mul_f32_e64 v41, v0, v41
	v_mul_f32_e64 v38, v0, v38
	v_mul_f32_e64 v39, v0, v39
	v_mul_f32_e64 v36, v0, v36
	v_mul_f32_e64 v37, v0, v37
	v_pk_mul_f32 v[34:35], v[0:1], v[34:35] op_sel_hi:[0,1]
	v_pk_mul_f32 v[32:33], v[0:1], v[32:33] op_sel_hi:[0,1]
	v_pk_mul_f32 v[30:31], v[0:1], v[30:31] op_sel_hi:[0,1]
	v_pk_mul_f32 v[28:29], v[0:1], v[28:29] op_sel_hi:[0,1]
	v_pk_mul_f32 v[26:27], v[0:1], v[26:27] op_sel_hi:[0,1]
	v_pk_mul_f32 v[24:25], v[0:1], v[24:25] op_sel_hi:[0,1]
	v_pk_mul_f32 v[22:23], v[0:1], v[22:23] op_sel_hi:[0,1]
	v_pk_mul_f32 v[20:21], v[0:1], v[20:21] op_sel_hi:[0,1]
	v_pk_mul_f32 v[18:19], v[0:1], v[18:19] op_sel_hi:[0,1]
	v_pk_mul_f32 v[16:17], v[0:1], v[16:17] op_sel_hi:[0,1]
	v_pk_mul_f32 v[14:15], v[0:1], v[14:15] op_sel_hi:[0,1]
	v_pk_mul_f32 v[12:13], v[0:1], v[12:13] op_sel_hi:[0,1]
	v_pk_mul_f32 v[10:11], v[0:1], v[10:11] op_sel_hi:[0,1]
	v_pk_mul_f32 v[8:9], v[0:1], v[8:9] op_sel_hi:[0,1]
	v_pk_mul_f32 v[6:7], v[0:1], v[6:7] op_sel_hi:[0,1]
	v_pk_mul_f32 v[4:5], v[0:1], v[4:5] op_sel_hi:[0,1]
	v_pk_mul_f32 v[2:3], v[0:1], v[2:3] op_sel_hi:[0,1]
	v_and_or_b32 v0, v80, 3, v152
	v_mov_b32_e32 v68, s10
	v_lshlrev_b32_e32 v150, 3, v74
	v_mad_u32_u24 v0, v0, s22, v68
	v_lshlrev_b32_e32 v68, 1, v74
	v_and_b32_e32 v67, 24, v150
	v_and_b32_e32 v68, 32, v68
	v_lshlrev_b32_e32 v66, 3, v148
	v_or3_b32 v0, v0, v68, v67
	s_addk_i32 s3, 0x4800
	v_add_u32_e32 v153, 0, v0
	v_sub_u32_e32 v154, s11, v152
	s_lshl_b32 s8, s17, 1
	v_lshlrev_b32_e32 v0, 1, v66
	ds_write_b128 v75, v[178:181] offset:46080
	ds_write_b128 v75, v[170:173] offset:55296
	s_waitcnt vmcnt(0)
	ds_write_b128 v75, v[204:207] offset:64512
	s_waitcnt lgkmcnt(0)
	s_barrier
	v_add_u32_e32 v251, s16, v149
	v_mul_lo_u32 v251, v251, s35
	v_add3_u32 v251, v251, s8, v0
	v_add_u32_e32 v251, 0x1c00, v251
	global_load_dwordx4 v[242:245], v251, s[6:7]
	global_load_dwordx4 v[246:249], v251, s[6:7] offset:32
	global_load_dwordx4 v[162:165], v251, s[6:7] offset:64
	global_load_dwordx4 v[166:169], v251, s[6:7] offset:96
	global_load_dwordx4 v[170:173], v251, s[6:7] offset:128
	global_load_dwordx4 v[174:177], v251, s[6:7] offset:160
	global_load_dwordx4 v[178:181], v251, s[6:7] offset:192
	global_load_dwordx4 v[186:189], v251, s[6:7] offset:224
.LBB0_392:
	v_add_u32_e32 v250, s2, v153
	ds_read_b64_tr_b16 v[218:219], v250
	ds_read_b64_tr_b16 v[220:221], v250 offset:4608
	ds_read_b64_tr_b16 v[222:223], v250 offset:64
	ds_read_b64_tr_b16 v[224:225], v250 offset:4672
	ds_read_b64_tr_b16 v[226:227], v250 offset:128
	ds_read_b64_tr_b16 v[228:229], v250 offset:4736
	ds_read_b64_tr_b16 v[230:231], v250 offset:192
	ds_read_b64_tr_b16 v[232:233], v250 offset:4800
	ds_read_b64_tr_b16 v[234:235], v250 offset:9216
	ds_read_b64_tr_b16 v[236:237], v250 offset:13824
	ds_read_b64_tr_b16 v[238:239], v250 offset:9280
	ds_read_b64_tr_b16 v[240:241], v250 offset:13888
	v_add_u32_e32 v155, v149, v154
	v_cmp_lt_i32_e32 vcc, -1, v155
	s_add_i32 s16, s16, 32
	v_subrev_u32_e32 v154, 32, v154
	s_waitcnt vmcnt(7)
	v_mfma_f32_32x32x16_bf16 v[66:81], v[242:245], v[82:85], 0
	s_waitcnt vmcnt(6)
	v_mfma_f32_32x32x16_bf16 v[66:81], v[246:249], v[86:89], v[66:81]
	v_cvt_f32_i32_e32 v156, v155
	v_mul_f32_e32 v156, v151, v156
	v_exp_f32_e32 v156, v156
	s_waitcnt vmcnt(5)
	v_mfma_f32_32x32x16_bf16 v[66:81], v[162:165], v[94:97], v[66:81]
	v_mul_f32_e32 v156, 0x3db504f3, v156
	s_waitcnt vmcnt(4)
	v_mfma_f32_32x32x16_bf16 v[66:81], v[166:169], v[98:101], v[66:81]
	s_waitcnt vmcnt(3)
	v_mfma_f32_32x32x16_bf16 v[66:81], v[170:173], v[102:105], v[66:81]
	s_waitcnt vmcnt(2)
	v_mfma_f32_32x32x16_bf16 v[66:81], v[174:177], v[106:109], v[66:81]
	s_waitcnt vmcnt(1)
	v_mfma_f32_32x32x16_bf16 v[66:81], v[178:181], v[110:113], v[66:81]
	s_waitcnt vmcnt(0)
	v_mfma_f32_32x32x16_bf16 v[66:81], v[186:189], v[90:93], v[66:81]
	s_add_i32 s10, s2, 0x4800
	s_cmp_lg_u32 s3, s10
	s_cbranch_scc0 .Lmu_nopf
	v_add_u32_e32 v251, 0x60000, v251
	global_load_dwordx4 v[242:245], v251, s[6:7]
	global_load_dwordx4 v[246:249], v251, s[6:7] offset:32
	global_load_dwordx4 v[162:165], v251, s[6:7] offset:64
	global_load_dwordx4 v[166:169], v251, s[6:7] offset:96
	global_load_dwordx4 v[170:173], v251, s[6:7] offset:128
	global_load_dwordx4 v[174:177], v251, s[6:7] offset:160
	global_load_dwordx4 v[178:181], v251, s[6:7] offset:192
	global_load_dwordx4 v[186:189], v251, s[6:7] offset:224
; #define LAS __attribute__((address_space(3)))
; #define MFMA32(a, b, c) __builtin_amdgcn_mfma_f32_32x32x16_bf16((a), (b), (c), 0, 0, 0)
; __device__ __forceinline__ int crow(int reg, int h) { return (reg & 3) + 8 * (reg >> 2) + 4 * h; }
; __device__ __forceinline__ s16x4 tr_read(const LAS unsigned char* p) { return __builtin_bit_cast(s16x4, __builtin_amdgcn_ds_read_tr16_b64_v4i16((LAS s16x4*)p)); }
; __device__ __forceinline__ bf16x8 cat8(s16x4 lo, s16x4 hi) { return __builtin_shufflevector(lo, hi, 0, 1, 2, 3, 4, 5, 6, 7); }
; __device__ __forceinline__ void main_unit(LAS unsigned char* lds, const bf16_t* __restrict__ proj, const bf16_t* __restrict__ sprevT, bf16_t* __restrict__ y,
;                                           const float* __restrict__ rnorm, int b, int h, int n) {
;     ...
; #pragma unroll
;         for (int i = 0; i < 16; ++i) {
;             const int d = iloc - (jt * 32 + crow(i, hh));
;             const float f = __builtin_amdgcn_exp2f(l2g * (float)d) * 0.08838834764831845f;
;             st[i] = d >= 0 ? st[i] * f : 0.f;
;         }
; #pragma unroll
;         for (int s2 = 0; s2 < 2; ++s2) {
;             const bf16x8 pb = pack_step(st, s2);
;             const LAS unsigned char* vp = va + (jt * 32 + 16 * s2) * VSTR;
; #pragma unroll
;             for (int t = 0; t < 4; ++t) { const bf16x8 a = cat8(tr_read(vp + t * 64), tr_read(vp + 8 * VSTR + t * 64)); acc[t] = MFMA32(a, pb, acc[t]); }
;         }
.Lmu_nopf:
	s_nop 11
	v_mul_f32_e32 v66, v156, v66
	v_add_u32_e32 v156, -1, v155
	v_cndmask_b32_e32 v66, 0, v66, vcc
	v_cmp_lt_i32_e32 vcc, -1, v156
	v_cvt_f32_i32_e32 v156, v156
	v_mul_f32_e32 v156, v151, v156
	v_exp_f32_e32 v156, v156
	s_nop 0
	v_mul_f32_e32 v156, 0x3db504f3, v156
	v_mul_f32_e32 v67, v156, v67
	v_add_u32_e32 v156, -2, v155
	v_cndmask_b32_e32 v67, 0, v67, vcc
	v_cmp_lt_i32_e32 vcc, -1, v156
	v_cvt_f32_i32_e32 v156, v156
	v_cvt_pk_bf16_f32 v66, v66, v67
	v_mul_f32_e32 v156, v151, v156
	v_exp_f32_e32 v156, v156
	s_nop 0
	v_mul_f32_e32 v156, 0x3db504f3, v156
	v_mul_f32_e32 v68, v156, v68
	v_add_u32_e32 v156, -3, v155
	v_cndmask_b32_e32 v68, 0, v68, vcc
	v_cmp_lt_i32_e32 vcc, -1, v156
	v_cvt_f32_i32_e32 v156, v156
	v_mul_f32_e32 v156, v151, v156
	v_exp_f32_e32 v156, v156
	s_nop 0
	v_mul_f32_e32 v156, 0x3db504f3, v156
	v_mul_f32_e32 v69, v156, v69
	v_add_u32_e32 v156, -8, v155
	v_cndmask_b32_e32 v69, 0, v69, vcc
	v_cmp_lt_i32_e32 vcc, -1, v156
	v_cvt_f32_i32_e32 v156, v156
	v_cvt_pk_bf16_f32 v67, v68, v69
	v_mul_f32_e32 v156, v151, v156
	v_exp_f32_e32 v156, v156
	s_nop 0
	v_mul_f32_e32 v156, 0x3db504f3, v156
	v_mul_f32_e32 v70, v156, v70
	v_add_u32_e32 v156, -9, v155
	v_cndmask_b32_e32 v70, 0, v70, vcc
	v_cmp_lt_i32_e32 vcc, -1, v156
	v_cvt_f32_i32_e32 v156, v156
	v_mul_f32_e32 v156, v151, v156
	v_exp_f32_e32 v156, v156
	s_nop 0
	v_mul_f32_e32 v156, 0x3db504f3, v156
	v_mul_f32_e32 v71, v156, v71
	v_add_u32_e32 v156, -10, v155
	v_cndmask_b32_e32 v71, 0, v71, vcc
	v_cmp_lt_i32_e32 vcc, -1, v156
	v_cvt_f32_i32_e32 v156, v156
	v_cvt_pk_bf16_f32 v68, v70, v71
	v_mul_f32_e32 v156, v151, v156
	v_exp_f32_e32 v156, v156
	s_nop 0
	v_mul_f32_e32 v156, 0x3db504f3, v156
	v_mul_f32_e32 v72, v156, v72
	v_add_u32_e32 v156, -11, v155
	v_cndmask_b32_e32 v72, 0, v72, vcc
	v_cmp_lt_i32_e32 vcc, -1, v156
	v_cvt_f32_i32_e32 v156, v156
	v_mul_f32_e32 v156, v151, v156
	v_exp_f32_e32 v156, v156
	s_nop 0
	v_mul_f32_e32 v156, 0x3db504f3, v156
	v_mul_f32_e32 v73, v156, v73
	v_add_u32_e32 v156, -16, v155
	v_cndmask_b32_e32 v73, 0, v73, vcc
	v_cmp_lt_i32_e32 vcc, -1, v156
	v_cvt_f32_i32_e32 v156, v156
	v_cvt_pk_bf16_f32 v69, v72, v73
	v_mul_f32_e32 v156, v151, v156
	v_exp_f32_e32 v156, v156
	s_nop 0
	v_mul_f32_e32 v156, 0x3db504f3, v156
	v_mul_f32_e32 v74, v156, v74
	v_subrev_u32_e32 v156, 17, v155
	v_cndmask_b32_e32 v74, 0, v74, vcc
	v_cmp_lt_i32_e32 vcc, -1, v156
	v_cvt_f32_i32_e32 v156, v156
	v_mul_f32_e32 v156, v151, v156
	v_exp_f32_e32 v156, v156
	s_nop 0
	v_mul_f32_e32 v156, 0x3db504f3, v156
	v_mul_f32_e32 v75, v156, v75
	v_subrev_u32_e32 v156, 18, v155
	v_cndmask_b32_e32 v75, 0, v75, vcc
	v_cmp_lt_i32_e32 vcc, -1, v156
	v_cvt_f32_i32_e32 v156, v156
	v_mul_f32_e32 v156, v151, v156
	v_exp_f32_e32 v156, v156
	s_nop 0
	v_mul_f32_e32 v156, 0x3db504f3, v156
	v_mul_f32_e32 v76, v156, v76
	v_subrev_u32_e32 v156, 19, v155
	v_cndmask_b32_e32 v76, 0, v76, vcc
	v_cmp_lt_i32_e32 vcc, -1, v156
	v_cvt_f32_i32_e32 v156, v156
	v_mul_f32_e32 v156, v151, v156
	v_exp_f32_e32 v156, v156
	s_nop 0
	v_mul_f32_e32 v156, 0x3db504f3, v156
	v_mul_f32_e32 v77, v156, v77
	v_subrev_u32_e32 v156, 24, v155
	v_cndmask_b32_e32 v77, 0, v77, vcc
	v_cmp_lt_i32_e32 vcc, -1, v156
	v_cvt_f32_i32_e32 v156, v156
	v_mul_f32_e32 v156, v151, v156
	v_exp_f32_e32 v156, v156
	s_nop 0
	v_mul_f32_e32 v156, 0x3db504f3, v156
	v_mul_f32_e32 v78, v156, v78
	v_subrev_u32_e32 v156, 25, v155
	v_cndmask_b32_e32 v78, 0, v78, vcc
	v_cmp_lt_i32_e32 vcc, -1, v156
	v_cvt_f32_i32_e32 v156, v156
	v_mul_f32_e32 v156, v151, v156
	v_exp_f32_e32 v156, v156
	s_nop 0
	v_mul_f32_e32 v156, 0x3db504f3, v156
	v_mul_f32_e32 v79, v156, v79
	v_subrev_u32_e32 v156, 26, v155
	v_cndmask_b32_e32 v79, 0, v79, vcc
	v_cmp_lt_i32_e32 vcc, -1, v156
	v_cvt_f32_i32_e32 v156, v156
	v_subrev_u32_e32 v155, 27, v155
	v_mul_f32_e32 v156, v151, v156
	v_exp_f32_e32 v156, v156
	s_nop 0
	v_mul_f32_e32 v156, 0x3db504f3, v156
	v_mul_f32_e32 v80, v156, v80
	v_cndmask_b32_e32 v80, 0, v80, vcc
	v_cmp_lt_i32_e32 vcc, -1, v155
	v_cvt_f32_i32_e32 v155, v155
	v_mul_f32_e32 v155, v151, v155
	v_exp_f32_e32 v155, v155
	s_nop 0
	v_mul_f32_e32 v155, 0x3db504f3, v155
	v_mul_f32_e32 v81, v155, v81
	v_add_u32_e32 v155, s2, v153
	s_waitcnt lgkmcnt(0)
	v_mfma_f32_32x32x16_bf16 v[50:65], v[218:221], v[66:69], v[50:65]
	v_cndmask_b32_e32 v81, 0, v81, vcc
	s_addk_i32 s2, 0x4800
	s_cmp_lg_u32 s3, s2
	s_waitcnt lgkmcnt(0)
	v_mfma_f32_32x32x16_bf16 v[34:49], v[222:225], v[66:69], v[34:49]
	ds_read_b64_tr_b16 v[218:219], v250 offset:9344
	ds_read_b64_tr_b16 v[220:221], v250 offset:13952
	ds_read_b64_tr_b16 v[222:223], v250 offset:9408
	ds_read_b64_tr_b16 v[224:225], v250 offset:14016
	s_waitcnt lgkmcnt(4)
	v_mfma_f32_32x32x16_bf16 v[18:33], v[226:229], v[66:69], v[18:33]
	s_waitcnt lgkmcnt(4)
	v_mfma_f32_32x32x16_bf16 v[2:17], v[230:233], v[66:69], v[2:17]
	v_cvt_pk_bf16_f32 v66, v74, v75
	v_cvt_pk_bf16_f32 v67, v76, v77
	v_cvt_pk_bf16_f32 v68, v78, v79
	v_cvt_pk_bf16_f32 v69, v80, v81
	s_waitcnt lgkmcnt(4)
	v_mfma_f32_32x32x16_bf16 v[50:65], v[234:237], v[66:69], v[50:65]
	s_waitcnt lgkmcnt(4)
	v_mfma_f32_32x32x16_bf16 v[34:49], v[238:241], v[66:69], v[34:49]
	s_waitcnt lgkmcnt(0)
	v_mfma_f32_32x32x16_bf16 v[18:33], v[218:221], v[66:69], v[18:33]
	s_waitcnt lgkmcnt(0)
	v_mfma_f32_32x32x16_bf16 v[2:17], v[222:225], v[66:69], v[2:17]
	s_cbranch_scc1 .LBB0_392
; #define LAS __attribute__((address_space(3)))
; __device__ __forceinline__ void main_unit(LAS unsigned char* lds, const bf16_t* __restrict__ proj, const bf16_t* __restrict__ sprevT, bf16_t* __restrict__ y,
;                                           const float* __restrict__ rnorm, int b, int h, int n) {
;     ...
;     float ss = 0.f;
; #pragma unroll
;     for (int t = 0; t < 4; ++t)
; #pragma unroll
;         for (int i = 0; i < 16; ++i) ss += acc[t][i] * acc[t][i];
;     ss += __shfl_xor(ss, 32);
;     LAS float* SS = (LAS float*)(lds + M_SS);
;     if (hh == 0) SS[dh * 128 + iloc] = ss;
	v_mul_f32_e32 v0, v51, v51
	v_fmac_f32_e32 v0, v50, v50
	v_fmac_f32_e32 v0, v52, v52
	v_fmac_f32_e32 v0, v53, v53
	v_fmac_f32_e32 v0, v54, v54
	v_fmac_f32_e32 v0, v55, v55
	v_fmac_f32_e32 v0, v56, v56
	v_fmac_f32_e32 v0, v57, v57
	v_fmac_f32_e32 v0, v58, v58
	v_fmac_f32_e32 v0, v59, v59
	v_fmac_f32_e32 v0, v60, v60
	v_fmac_f32_e32 v0, v61, v61
	v_fmac_f32_e32 v0, v62, v62
	v_fmac_f32_e32 v0, v63, v63
	v_fmac_f32_e32 v0, v64, v64
	v_fmac_f32_e32 v0, v65, v65
	v_fmac_f32_e32 v0, v34, v34
	v_fmac_f32_e32 v0, v35, v35
	v_fmac_f32_e32 v0, v36, v36
	v_fmac_f32_e32 v0, v37, v37
	v_fmac_f32_e32 v0, v38, v38
	v_fmac_f32_e32 v0, v39, v39
	v_fmac_f32_e32 v0, v40, v40
	v_fmac_f32_e32 v0, v41, v41
	v_fmac_f32_e32 v0, v42, v42
	v_fmac_f32_e32 v0, v43, v43
	v_fmac_f32_e32 v0, v44, v44
	v_fmac_f32_e32 v0, v45, v45
	v_fmac_f32_e32 v0, v46, v46
	v_fmac_f32_e32 v0, v47, v47
	v_fmac_f32_e32 v0, v48, v48
	v_fmac_f32_e32 v0, v49, v49
	v_fmac_f32_e32 v0, v18, v18
	v_fmac_f32_e32 v0, v19, v19
	v_fmac_f32_e32 v0, v20, v20
	v_fmac_f32_e32 v0, v21, v21
	v_fmac_f32_e32 v0, v22, v22
	v_fmac_f32_e32 v0, v23, v23
	v_fmac_f32_e32 v0, v24, v24
	v_fmac_f32_e32 v0, v25, v25
	v_fmac_f32_e32 v0, v26, v26
	v_fmac_f32_e32 v0, v27, v27
	v_fmac_f32_e32 v0, v28, v28
	v_fmac_f32_e32 v0, v29, v29
	v_fmac_f32_e32 v0, v30, v30
	v_fmac_f32_e32 v0, v31, v31
	v_fmac_f32_e32 v0, v32, v32
	v_fmac_f32_e32 v0, v33, v33
	v_fmac_f32_e32 v0, v2, v2
	v_fmac_f32_e32 v0, v3, v3
	v_fmac_f32_e32 v0, v4, v4
	v_fmac_f32_e32 v0, v5, v5
	v_fmac_f32_e32 v0, v6, v6
	v_fmac_f32_e32 v0, v7, v7
	v_fmac_f32_e32 v0, v8, v8
	v_fmac_f32_e32 v0, v9, v9
	v_fmac_f32_e32 v0, v10, v10
	v_fmac_f32_e32 v0, v11, v11
	v_fmac_f32_e32 v0, v12, v12
	v_fmac_f32_e32 v0, v13, v13
	v_fmac_f32_e32 v0, v14, v14
	v_fmac_f32_e32 v0, v15, v15
	v_fmac_f32_e32 v0, v16, v16
	v_fmac_f32_e32 v0, v17, v17
	ds_bpermute_b32 v66, v215, v0
	v_cmp_eq_u32_e32 vcc, 0, v148
	s_and_saveexec_b64 s[16:17], vcc
	s_cbranch_execz .LBB0_395
	s_lshl_b32 s2, s1, 2
	s_add_i32 s2, s2, 0
	s_waitcnt lgkmcnt(0)
	v_add_f32_e32 v0, v0, v66
	v_lshl_add_u32 v66, v145, 2, s2
	v_add_u32_e32 v66, 0x20800, v66
	ds_write_b32 v66, v0
